# gate phase: statistics loads first, then all tile loads ahead of the first barrier, counted vmcnt per consumer
# baseline (speedup 1.0000x reference)
.LBB0_190:
	s_ashr_i32 s12, s42, 4
	s_and_b32 s16, s42, 7
	s_and_b32 s17, s12, 0x7ffffff8
	s_or_b32 s16, s17, s16
	s_lshl_b32 s16, s16, 1
	s_bfe_u32 s17, s42, 0x10006
	s_or_b32 s16, s16, s17
	s_and_saveexec_b64 s[18:19], s[4:5]
	s_cbranch_execz .Lg3_190_nl
	v_lshl_add_u32 v0, s16, 7, v153
	v_ashrrev_i32_e32 v1, 31, v0
	v_lshlrev_b64 v[0:1], 8, v[0:1]
	v_lshl_add_u64 v[60:61], s[10:11], 0, v[0:1]
	global_load_dwordx4 v[0:3], v[60:61], off
	global_load_dwordx4 v[4:7], v[60:61], off offset:16
	global_load_dwordx4 v[8:11], v[60:61], off offset:32
	global_load_dwordx4 v[12:15], v[60:61], off offset:48
	global_load_dwordx4 v[16:19], v[60:61], off offset:64
	global_load_dwordx4 v[20:23], v[60:61], off offset:80
	global_load_dwordx4 v[24:27], v[60:61], off offset:96
	global_load_dwordx4 v[28:31], v[60:61], off offset:112
	global_load_dwordx4 v[32:35], v[60:61], off offset:128
	global_load_dwordx4 v[36:39], v[60:61], off offset:144
	global_load_dwordx4 v[40:43], v[60:61], off offset:160
	global_load_dwordx4 v[44:47], v[60:61], off offset:176
	global_load_dwordx4 v[48:51], v[60:61], off offset:192
	global_load_dwordx4 v[52:55], v[60:61], off offset:208
	global_load_dwordx4 v[56:59], v[60:61], off offset:224
	s_nop 0
	global_load_dwordx4 v[60:63], v[60:61], off offset:240
.Lg3_190_nl:
	s_or_b64 exec, exec, s[18:19]
	s_lshl_b32 s18, s42, 4
	s_and_b32 s18, s18, 0x380
	v_add_u32_e32 v248, s18, v148
	v_ashrrev_i32_e32 v249, 31, v248
	v_lshlrev_b64 v[248:249], 9, v[248:249]
	v_lshl_add_u64 v[248:249], v[164:165], 0, v[248:249]
	global_load_dwordx4 v[96:99], v[248:249], off
	global_load_dwordx4 v[100:103], v[248:249], off offset:16
	global_load_dwordx4 v[104:107], v[248:249], off offset:32
	global_load_dwordx4 v[108:111], v[248:249], off offset:48
	global_load_dwordx4 v[112:115], v[248:249], off offset:64
	global_load_dwordx4 v[116:119], v[248:249], off offset:80
	global_load_dwordx4 v[120:123], v[248:249], off offset:96
	global_load_dwordx4 v[124:127], v[248:249], off offset:112
	s_lshr_b32 s19, s42, 3
	s_and_b32 s19, s19, 7
	s_lshl_b32 s18, s16, 11
	s_lshl_b32 s22, s19, 8
	s_or_b32 s18, s18, s22
	v_ashrrev_i32_e32 v250, 4, v153
	v_add_u32_e32 v250, s18, v250
	v_mov_b32_e32 v251, 0
	v_lshlrev_b64 v[250:251], 8, v[250:251]
	v_lshl_add_u64 v[250:251], v[150:151], 0, v[250:251]
	s_movk_i32 s22, 0x2000
	s_mov_b32 s23, 0
	global_load_dwordx4 v[64:67], v[250:251], off
	v_lshl_add_u64 v[250:251], v[250:251], 0, s[22:23]
	global_load_dwordx4 v[68:71], v[250:251], off
	v_lshl_add_u64 v[250:251], v[250:251], 0, s[22:23]
	global_load_dwordx4 v[72:75], v[250:251], off
	v_lshl_add_u64 v[250:251], v[250:251], 0, s[22:23]
	global_load_dwordx4 v[76:79], v[250:251], off
	v_lshl_add_u64 v[250:251], v[250:251], 0, s[22:23]
	global_load_dwordx4 v[80:83], v[250:251], off
	v_lshl_add_u64 v[250:251], v[250:251], 0, s[22:23]
	global_load_dwordx4 v[84:87], v[250:251], off
	v_lshl_add_u64 v[250:251], v[250:251], 0, s[22:23]
	global_load_dwordx4 v[88:91], v[250:251], off
	v_lshl_add_u64 v[250:251], v[250:251], 0, s[22:23]
	global_load_dwordx4 v[92:95], v[250:251], off
	v_lshl_add_u32 v248, s16, 7, v178
	v_ashrrev_i32_e32 v249, 31, v248
	v_lshlrev_b64 v[248:249], 12, v[248:249]
	v_lshl_or_b32 v248, s19, 9, v248
	v_lshl_add_u64 v[248:249], v[166:167], 0, v[248:249]
	s_mov_b32 s22, 0x6000000
	v_lshl_add_u64 v[248:249], v[248:249], 0, s[22:23]
	s_mov_b32 s22, 0x8000
	global_load_dwordx4 v[216:219], v[248:249], off
	v_lshl_add_u64 v[248:249], v[248:249], 0, s[22:23]
	global_load_dwordx4 v[220:223], v[248:249], off
	v_lshl_add_u64 v[248:249], v[248:249], 0, s[22:23]
	global_load_dwordx4 v[224:227], v[248:249], off
	v_lshl_add_u64 v[248:249], v[248:249], 0, s[22:23]
	global_load_dwordx4 v[228:231], v[248:249], off
	v_lshl_add_u64 v[248:249], v[248:249], 0, s[22:23]
	global_load_dwordx4 v[232:235], v[248:249], off
	v_lshl_add_u64 v[248:249], v[248:249], 0, s[22:23]
	global_load_dwordx4 v[236:239], v[248:249], off
	v_lshl_add_u64 v[248:249], v[248:249], 0, s[22:23]
	global_load_dwordx4 v[240:243], v[248:249], off
	v_lshl_add_u64 v[248:249], v[248:249], 0, s[22:23]
	global_load_dwordx4 v[244:247], v[248:249], off
	s_waitcnt lgkmcnt(0)
	s_barrier
	s_and_saveexec_b64 s[18:19], s[4:5]
	s_cbranch_execz .LBB0_192
	s_waitcnt vmcnt(39)
	v_pk_add_f32 v[0:1], v[0:1], 0 op_sel_hi:[1,0]
	s_nop 0
	v_pk_add_f32 v[0:1], v[0:1], v[2:3]
	s_waitcnt vmcnt(38)
	v_pk_add_f32 v[0:1], v[0:1], v[4:5]
	s_nop 0
	v_pk_add_f32 v[0:1], v[0:1], v[6:7]
	s_waitcnt vmcnt(37)
	v_pk_add_f32 v[0:1], v[0:1], v[8:9]
	s_nop 0
	v_pk_add_f32 v[0:1], v[0:1], v[10:11]
	s_waitcnt vmcnt(36)
	v_pk_add_f32 v[0:1], v[0:1], v[12:13]
	s_nop 0
	v_pk_add_f32 v[0:1], v[0:1], v[14:15]
	s_waitcnt vmcnt(35)
	v_pk_add_f32 v[0:1], v[0:1], v[16:17]
	s_nop 0
	v_pk_add_f32 v[0:1], v[0:1], v[18:19]
	s_waitcnt vmcnt(34)
	v_pk_add_f32 v[0:1], v[0:1], v[20:21]
	s_nop 0
	v_pk_add_f32 v[0:1], v[0:1], v[22:23]
	s_waitcnt vmcnt(33)
	v_pk_add_f32 v[0:1], v[0:1], v[24:25]
	s_nop 0
	v_pk_add_f32 v[0:1], v[0:1], v[26:27]
	s_waitcnt vmcnt(32)
	v_pk_add_f32 v[0:1], v[0:1], v[28:29]
	s_nop 0
	v_pk_add_f32 v[0:1], v[0:1], v[30:31]
	s_waitcnt vmcnt(31)
	v_pk_add_f32 v[0:1], v[0:1], v[32:33]
	s_nop 0
	v_pk_add_f32 v[0:1], v[0:1], v[34:35]
	s_waitcnt vmcnt(30)
	v_pk_add_f32 v[0:1], v[0:1], v[36:37]
	s_nop 0
	v_pk_add_f32 v[0:1], v[0:1], v[38:39]
	s_waitcnt vmcnt(29)
	v_pk_add_f32 v[0:1], v[0:1], v[40:41]
	s_nop 0
	v_pk_add_f32 v[0:1], v[0:1], v[42:43]
	s_waitcnt vmcnt(28)
	v_pk_add_f32 v[0:1], v[0:1], v[44:45]
	s_nop 0
	v_pk_add_f32 v[0:1], v[0:1], v[46:47]
	s_waitcnt vmcnt(27)
	v_pk_add_f32 v[0:1], v[0:1], v[48:49]
	s_nop 0
	v_pk_add_f32 v[0:1], v[0:1], v[50:51]
	s_waitcnt vmcnt(26)
	v_pk_add_f32 v[0:1], v[0:1], v[52:53]
	s_nop 0
	v_pk_add_f32 v[0:1], v[0:1], v[54:55]
	s_waitcnt vmcnt(25)
	v_pk_add_f32 v[0:1], v[0:1], v[56:57]
	s_nop 0
	v_pk_add_f32 v[0:1], v[0:1], v[58:59]
	s_waitcnt vmcnt(24)
	v_pk_add_f32 v[0:1], v[0:1], v[60:61]
	s_nop 0
	v_pk_add_f32 v[0:1], v[0:1], v[62:63]
	s_nop 0
	v_pk_mul_f32 v[0:1], v[0:1], s[14:15] op_sel_hi:[1,0]
	s_nop 0
	v_fma_f32 v1, -v0, v0, v1
	v_max_f32_e32 v1, 0, v1
	v_add_f32_e32 v1, 0x358637bd, v1
	v_mul_f32_e32 v2, 0x4b800000, v1
	v_cmp_gt_f32_e32 vcc, s40, v1
	s_nop 1
	v_cndmask_b32_e32 v1, v1, v2, vcc
	v_rsq_f32_e32 v1, v1
	s_nop 0
	v_mul_f32_e32 v2, 0x45800000, v1
	v_cndmask_b32_e32 v1, v1, v2, vcc
	ds_write2st64_b32 v172, v0, v1 offset1:2
.LBB0_192:
	s_or_b64 exec, exec, s[18:19]
	s_lshl_b32 s18, s42, 4
	s_and_b32 s18, s18, 0x380
	v_add_u32_e32 v0, s18, v148
	v_ashrrev_i32_e32 v1, 31, v0
	v_lshlrev_b64 v[0:1], 9, v[0:1]
	v_mov_b32_e32 v10, 0
	s_lshr_b32 s43, s42, 6
	s_lshr_b32 s17, s42, 3
	v_lshl_add_u64 v[8:9], v[164:165], 0, v[0:1]
	s_mov_b64 s[18:19], 0
	v_mov_b32_e32 v7, v191
	v_mov_b32_e32 v16, v173
	v_mov_b32_e32 v17, v174
	v_mov_b32_e32 v11, v10
	s_waitcnt lgkmcnt(0)
	s_barrier
	s_waitcnt vmcnt(16)
	v_cmp_le_i32_e32 vcc, v16, v148
	v_mov_b32_e32 v0, v97
	v_mov_b32_e32 v1, v98
	v_mov_b32_e32 v2, v99
	v_mov_b32_e32 v3, v100
	v_mov_b32_e32 v4, v101
	v_mov_b32_e32 v5, v102
	v_mov_b32_e32 v6, v103
	v_cndmask_b32_e32 v12, 0, v96, vcc
	ds_read2st64_b64 v[18:21], v7 offset1:1
	v_cmp_lt_i32_e32 vcc, v16, v148
	s_add_u32 s18, s18, 32
	s_addc_u32 s19, s19, 0
	s_waitcnt vmcnt(16)
	v_cndmask_b32_e32 v13, 0, v0, vcc
	s_waitcnt lgkmcnt(0)
	v_pk_mul_f32 v[14:15], v[12:13], v[20:21]
	s_cmpk_eq_i32 s18, 0x80
	v_cvt_pk_bf16_f32 v0, v14, v15
	v_and_b32_e32 v32, 0xffff0000, v0
	v_lshlrev_b32_e32 v33, 16, v0
	v_or_b32_e32 v0, 3, v16
	v_or_b32_e32 v14, 2, v16
	v_cmp_le_i32_e32 vcc, v0, v149
	v_mul_f32_e32 v15, v18, v33
	v_lshl_add_u32 v18, v14, 2, s3
	v_cndmask_b32_e32 v21, 0, v2, vcc
	v_cmp_le_i32_e32 vcc, v14, v148
	v_lshl_add_u32 v22, v0, 2, s3
	v_or_b32_e32 v2, 4, v16
	v_cndmask_b32_e32 v20, 0, v1, vcc
	ds_read_b64 v[0:1], v18 offset:512
	v_lshl_add_u32 v14, v2, 2, s3
	ds_read_b32 v18, v18
	ds_read_b32 v22, v22
	ds_read_b32 v28, v14
	v_mul_f32_e32 v19, v19, v32
	v_add_u32_e32 v7, 32, v7
	s_waitcnt lgkmcnt(3)
	v_pk_mul_f32 v[0:1], v[20:21], v[0:1]
	s_nop 0
	v_cvt_pk_bf16_f32 v0, v0, v1
	v_and_b32_e32 v34, 0xffff0000, v0
	v_lshlrev_b32_e32 v35, 16, v0
	v_or_b32_e32 v0, 5, v16
	v_cmp_le_i32_e32 vcc, v0, v149
	s_waitcnt lgkmcnt(2)
	v_mul_f32_e32 v1, v18, v35
	v_lshl_add_u32 v18, v0, 2, s3
	v_cndmask_b32_e32 v25, 0, v4, vcc
	v_cmp_le_i32_e32 vcc, v2, v148
	v_or_b32_e32 v0, 6, v16
	v_lshl_add_u32 v4, v0, 2, s3
	v_cndmask_b32_e32 v24, 0, v3, vcc
	ds_read_b64 v[2:3], v14 offset:512
	ds_read_b32 v14, v18
	ds_read_b32 v18, v4
	ds_read_b64 v[26:27], v4 offset:512
	s_waitcnt lgkmcnt(5)
	v_mul_f32_e32 v23, v22, v34
	v_mov_b32_e32 v22, v21
	s_waitcnt lgkmcnt(3)
	v_pk_mul_f32 v[2:3], v[24:25], v[2:3]
	s_nop 0
	v_cvt_pk_bf16_f32 v2, v2, v3
	v_and_b32_e32 v36, 0xffff0000, v2
	v_lshlrev_b32_e32 v37, 16, v2
	v_or_b32_e32 v2, 7, v16
	v_cmp_le_i32_e32 vcc, v2, v149
	s_waitcnt lgkmcnt(2)
	v_mul_f32_e32 v29, v14, v36
	v_mov_b32_e32 v14, v12
	v_cndmask_b32_e32 v31, 0, v6, vcc
	v_cmp_le_i32_e32 vcc, v0, v148
	v_pk_add_f32 v[10:11], v[10:11], v[14:15]
	v_mul_f32_e32 v3, v28, v37
	v_cndmask_b32_e32 v30, 0, v5, vcc
	s_waitcnt lgkmcnt(0)
	v_pk_mul_f32 v[4:5], v[30:31], v[26:27]
	v_lshl_add_u32 v28, v2, 2, s3
	v_cvt_pk_bf16_f32 v0, v4, v5
	v_lshlrev_b32_e32 v26, 16, v0
	v_mul_f32_e32 v5, v18, v26
	v_mov_b32_e32 v18, v13
	v_and_b32_e32 v6, 0xffff0000, v0
	v_pk_add_f32 v[10:11], v[18:19], v[10:11]
	v_mov_b32_e32 v0, v20
	v_pk_add_f32 v[0:1], v[0:1], v[10:11]
	v_mov_b32_e32 v2, v24
	v_pk_add_f32 v[0:1], v[22:23], v[0:1]
	v_mov_b32_e32 v4, v30
	v_pk_add_f32 v[0:1], v[2:3], v[0:1]
	ds_read_b32 v2, v28
	v_mov_b32_e32 v28, v25
	v_pk_add_f32 v[0:1], v[28:29], v[0:1]
	v_add_u32_e32 v16, 8, v16
	v_pk_add_f32 v[0:1], v[4:5], v[0:1]
	s_waitcnt lgkmcnt(0)
	v_mul_f32_e32 v3, v2, v6
	v_mov_b32_e32 v2, v31
	v_pk_add_f32 v[10:11], v[2:3], v[0:1]
	v_cvt_pk_bf16_f32 v0, v33, v32
	v_cvt_pk_bf16_f32 v1, v35, v34
	v_cvt_pk_bf16_f32 v2, v37, v36
	v_cvt_pk_bf16_f32 v3, v26, v6
	ds_write_b128 v17, v[0:3]
	v_add_u32_e32 v17, 16, v17
	v_cmp_le_i32_e32 vcc, v16, v148
	v_mov_b32_e32 v0, v105
	v_mov_b32_e32 v1, v106
	v_mov_b32_e32 v2, v107
	v_mov_b32_e32 v3, v108
	v_mov_b32_e32 v4, v109
	v_mov_b32_e32 v5, v110
	v_mov_b32_e32 v6, v111
	v_cndmask_b32_e32 v12, 0, v104, vcc
	ds_read2st64_b64 v[18:21], v7 offset1:1
	v_cmp_lt_i32_e32 vcc, v16, v148
	s_add_u32 s18, s18, 32
	s_addc_u32 s19, s19, 0
	s_waitcnt vmcnt(16)
	v_cndmask_b32_e32 v13, 0, v0, vcc
	s_waitcnt lgkmcnt(0)
	v_pk_mul_f32 v[14:15], v[12:13], v[20:21]
	s_cmpk_eq_i32 s18, 0x80
	v_cvt_pk_bf16_f32 v0, v14, v15
	v_and_b32_e32 v32, 0xffff0000, v0
	v_lshlrev_b32_e32 v33, 16, v0
	v_or_b32_e32 v0, 3, v16
	v_or_b32_e32 v14, 2, v16
	v_cmp_le_i32_e32 vcc, v0, v149
	v_mul_f32_e32 v15, v18, v33
	v_lshl_add_u32 v18, v14, 2, s3
	v_cndmask_b32_e32 v21, 0, v2, vcc
	v_cmp_le_i32_e32 vcc, v14, v148
	v_lshl_add_u32 v22, v0, 2, s3
	v_or_b32_e32 v2, 4, v16
	v_cndmask_b32_e32 v20, 0, v1, vcc
	ds_read_b64 v[0:1], v18 offset:512
	v_lshl_add_u32 v14, v2, 2, s3
	ds_read_b32 v18, v18
	ds_read_b32 v22, v22
	ds_read_b32 v28, v14
	v_mul_f32_e32 v19, v19, v32
	v_add_u32_e32 v7, 32, v7
	s_waitcnt lgkmcnt(3)
	v_pk_mul_f32 v[0:1], v[20:21], v[0:1]
	s_nop 0
	v_cvt_pk_bf16_f32 v0, v0, v1
	v_and_b32_e32 v34, 0xffff0000, v0
	v_lshlrev_b32_e32 v35, 16, v0
	v_or_b32_e32 v0, 5, v16
	v_cmp_le_i32_e32 vcc, v0, v149
	s_waitcnt lgkmcnt(2)
	v_mul_f32_e32 v1, v18, v35
	v_lshl_add_u32 v18, v0, 2, s3
	v_cndmask_b32_e32 v25, 0, v4, vcc
	v_cmp_le_i32_e32 vcc, v2, v148
	v_or_b32_e32 v0, 6, v16
	v_lshl_add_u32 v4, v0, 2, s3
	v_cndmask_b32_e32 v24, 0, v3, vcc
	ds_read_b64 v[2:3], v14 offset:512
	ds_read_b32 v14, v18
	ds_read_b32 v18, v4
	ds_read_b64 v[26:27], v4 offset:512
	s_waitcnt lgkmcnt(5)
	v_mul_f32_e32 v23, v22, v34
	v_mov_b32_e32 v22, v21
	s_waitcnt lgkmcnt(3)
	v_pk_mul_f32 v[2:3], v[24:25], v[2:3]
	s_nop 0
	v_cvt_pk_bf16_f32 v2, v2, v3
	v_and_b32_e32 v36, 0xffff0000, v2
	v_lshlrev_b32_e32 v37, 16, v2
	v_or_b32_e32 v2, 7, v16
	v_cmp_le_i32_e32 vcc, v2, v149
	s_waitcnt lgkmcnt(2)
	v_mul_f32_e32 v29, v14, v36
	v_mov_b32_e32 v14, v12
	v_cndmask_b32_e32 v31, 0, v6, vcc
	v_cmp_le_i32_e32 vcc, v0, v148
	v_pk_add_f32 v[10:11], v[10:11], v[14:15]
	v_mul_f32_e32 v3, v28, v37
	v_cndmask_b32_e32 v30, 0, v5, vcc
	s_waitcnt lgkmcnt(0)
	v_pk_mul_f32 v[4:5], v[30:31], v[26:27]
	v_lshl_add_u32 v28, v2, 2, s3
	v_cvt_pk_bf16_f32 v0, v4, v5
	v_lshlrev_b32_e32 v26, 16, v0
	v_mul_f32_e32 v5, v18, v26
	v_mov_b32_e32 v18, v13
	v_and_b32_e32 v6, 0xffff0000, v0
	v_pk_add_f32 v[10:11], v[18:19], v[10:11]
	v_mov_b32_e32 v0, v20
	v_pk_add_f32 v[0:1], v[0:1], v[10:11]
	v_mov_b32_e32 v2, v24
	v_pk_add_f32 v[0:1], v[22:23], v[0:1]
	v_mov_b32_e32 v4, v30
	v_pk_add_f32 v[0:1], v[2:3], v[0:1]
	ds_read_b32 v2, v28
	v_mov_b32_e32 v28, v25
	v_pk_add_f32 v[0:1], v[28:29], v[0:1]
	v_add_u32_e32 v16, 8, v16
	v_pk_add_f32 v[0:1], v[4:5], v[0:1]
	s_waitcnt lgkmcnt(0)
	v_mul_f32_e32 v3, v2, v6
	v_mov_b32_e32 v2, v31
	v_pk_add_f32 v[10:11], v[2:3], v[0:1]
	v_cvt_pk_bf16_f32 v0, v33, v32
	v_cvt_pk_bf16_f32 v1, v35, v34
	v_cvt_pk_bf16_f32 v2, v37, v36
	v_cvt_pk_bf16_f32 v3, v26, v6
	ds_write_b128 v17, v[0:3]
	v_add_u32_e32 v17, 16, v17
	v_cmp_le_i32_e32 vcc, v16, v148
	v_mov_b32_e32 v0, v113
	v_mov_b32_e32 v1, v114
	v_mov_b32_e32 v2, v115
	v_mov_b32_e32 v3, v116
	v_mov_b32_e32 v4, v117
	v_mov_b32_e32 v5, v118
	v_mov_b32_e32 v6, v119
	v_cndmask_b32_e32 v12, 0, v112, vcc
	ds_read2st64_b64 v[18:21], v7 offset1:1
	v_cmp_lt_i32_e32 vcc, v16, v148
	s_add_u32 s18, s18, 32
	s_addc_u32 s19, s19, 0
	s_waitcnt vmcnt(16)
	v_cndmask_b32_e32 v13, 0, v0, vcc
	s_waitcnt lgkmcnt(0)
	v_pk_mul_f32 v[14:15], v[12:13], v[20:21]
	s_cmpk_eq_i32 s18, 0x80
	v_cvt_pk_bf16_f32 v0, v14, v15
	v_and_b32_e32 v32, 0xffff0000, v0
	v_lshlrev_b32_e32 v33, 16, v0
	v_or_b32_e32 v0, 3, v16
	v_or_b32_e32 v14, 2, v16
	v_cmp_le_i32_e32 vcc, v0, v149
	v_mul_f32_e32 v15, v18, v33
	v_lshl_add_u32 v18, v14, 2, s3
	v_cndmask_b32_e32 v21, 0, v2, vcc
	v_cmp_le_i32_e32 vcc, v14, v148
	v_lshl_add_u32 v22, v0, 2, s3
	v_or_b32_e32 v2, 4, v16
	v_cndmask_b32_e32 v20, 0, v1, vcc
	ds_read_b64 v[0:1], v18 offset:512
	v_lshl_add_u32 v14, v2, 2, s3
	ds_read_b32 v18, v18
	ds_read_b32 v22, v22
	ds_read_b32 v28, v14
	v_mul_f32_e32 v19, v19, v32
	v_add_u32_e32 v7, 32, v7
	s_waitcnt lgkmcnt(3)
	v_pk_mul_f32 v[0:1], v[20:21], v[0:1]
	s_nop 0
	v_cvt_pk_bf16_f32 v0, v0, v1
	v_and_b32_e32 v34, 0xffff0000, v0
	v_lshlrev_b32_e32 v35, 16, v0
	v_or_b32_e32 v0, 5, v16
	v_cmp_le_i32_e32 vcc, v0, v149
	s_waitcnt lgkmcnt(2)
	v_mul_f32_e32 v1, v18, v35
	v_lshl_add_u32 v18, v0, 2, s3
	v_cndmask_b32_e32 v25, 0, v4, vcc
	v_cmp_le_i32_e32 vcc, v2, v148
	v_or_b32_e32 v0, 6, v16
	v_lshl_add_u32 v4, v0, 2, s3
	v_cndmask_b32_e32 v24, 0, v3, vcc
	ds_read_b64 v[2:3], v14 offset:512
	ds_read_b32 v14, v18
	ds_read_b32 v18, v4
	ds_read_b64 v[26:27], v4 offset:512
	s_waitcnt lgkmcnt(5)
	v_mul_f32_e32 v23, v22, v34
	v_mov_b32_e32 v22, v21
	s_waitcnt lgkmcnt(3)
	v_pk_mul_f32 v[2:3], v[24:25], v[2:3]
	s_nop 0
	v_cvt_pk_bf16_f32 v2, v2, v3
	v_and_b32_e32 v36, 0xffff0000, v2
	v_lshlrev_b32_e32 v37, 16, v2
	v_or_b32_e32 v2, 7, v16
	v_cmp_le_i32_e32 vcc, v2, v149
	s_waitcnt lgkmcnt(2)
	v_mul_f32_e32 v29, v14, v36
	v_mov_b32_e32 v14, v12
	v_cndmask_b32_e32 v31, 0, v6, vcc
	v_cmp_le_i32_e32 vcc, v0, v148
	v_pk_add_f32 v[10:11], v[10:11], v[14:15]
	v_mul_f32_e32 v3, v28, v37
	v_cndmask_b32_e32 v30, 0, v5, vcc
	s_waitcnt lgkmcnt(0)
	v_pk_mul_f32 v[4:5], v[30:31], v[26:27]
	v_lshl_add_u32 v28, v2, 2, s3
	v_cvt_pk_bf16_f32 v0, v4, v5
	v_lshlrev_b32_e32 v26, 16, v0
	v_mul_f32_e32 v5, v18, v26
	v_mov_b32_e32 v18, v13
	v_and_b32_e32 v6, 0xffff0000, v0
	v_pk_add_f32 v[10:11], v[18:19], v[10:11]
	v_mov_b32_e32 v0, v20
	v_pk_add_f32 v[0:1], v[0:1], v[10:11]
	v_mov_b32_e32 v2, v24
	v_pk_add_f32 v[0:1], v[22:23], v[0:1]
	v_mov_b32_e32 v4, v30
	v_pk_add_f32 v[0:1], v[2:3], v[0:1]
	ds_read_b32 v2, v28
	v_mov_b32_e32 v28, v25
	v_pk_add_f32 v[0:1], v[28:29], v[0:1]
	v_add_u32_e32 v16, 8, v16
	v_pk_add_f32 v[0:1], v[4:5], v[0:1]
	s_waitcnt lgkmcnt(0)
	v_mul_f32_e32 v3, v2, v6
	v_mov_b32_e32 v2, v31
	v_pk_add_f32 v[10:11], v[2:3], v[0:1]
	v_cvt_pk_bf16_f32 v0, v33, v32
	v_cvt_pk_bf16_f32 v1, v35, v34
	v_cvt_pk_bf16_f32 v2, v37, v36
	v_cvt_pk_bf16_f32 v3, v26, v6
	ds_write_b128 v17, v[0:3]
	v_add_u32_e32 v17, 16, v17
	v_cmp_le_i32_e32 vcc, v16, v148
	v_mov_b32_e32 v0, v121
	v_mov_b32_e32 v1, v122
	v_mov_b32_e32 v2, v123
	v_mov_b32_e32 v3, v124
	v_mov_b32_e32 v4, v125
	v_mov_b32_e32 v5, v126
	v_mov_b32_e32 v6, v127
	v_cndmask_b32_e32 v12, 0, v120, vcc
	ds_read2st64_b64 v[18:21], v7 offset1:1
	v_cmp_lt_i32_e32 vcc, v16, v148
	s_add_u32 s18, s18, 32
	s_addc_u32 s19, s19, 0
	s_waitcnt vmcnt(16)
	v_cndmask_b32_e32 v13, 0, v0, vcc
	s_waitcnt lgkmcnt(0)
	v_pk_mul_f32 v[14:15], v[12:13], v[20:21]
	s_cmpk_eq_i32 s18, 0x80
	v_cvt_pk_bf16_f32 v0, v14, v15
	v_and_b32_e32 v32, 0xffff0000, v0
	v_lshlrev_b32_e32 v33, 16, v0
	v_or_b32_e32 v0, 3, v16
	v_or_b32_e32 v14, 2, v16
	v_cmp_le_i32_e32 vcc, v0, v149
	v_mul_f32_e32 v15, v18, v33
	v_lshl_add_u32 v18, v14, 2, s3
	v_cndmask_b32_e32 v21, 0, v2, vcc
	v_cmp_le_i32_e32 vcc, v14, v148
	v_lshl_add_u32 v22, v0, 2, s3
	v_or_b32_e32 v2, 4, v16
	v_cndmask_b32_e32 v20, 0, v1, vcc
	ds_read_b64 v[0:1], v18 offset:512
	v_lshl_add_u32 v14, v2, 2, s3
	ds_read_b32 v18, v18
	ds_read_b32 v22, v22
	ds_read_b32 v28, v14
	v_mul_f32_e32 v19, v19, v32
	v_add_u32_e32 v7, 32, v7
	s_waitcnt lgkmcnt(3)
	v_pk_mul_f32 v[0:1], v[20:21], v[0:1]
	s_nop 0
	v_cvt_pk_bf16_f32 v0, v0, v1
	v_and_b32_e32 v34, 0xffff0000, v0
	v_lshlrev_b32_e32 v35, 16, v0
	v_or_b32_e32 v0, 5, v16
	v_cmp_le_i32_e32 vcc, v0, v149
	s_waitcnt lgkmcnt(2)
	v_mul_f32_e32 v1, v18, v35
	v_lshl_add_u32 v18, v0, 2, s3
	v_cndmask_b32_e32 v25, 0, v4, vcc
	v_cmp_le_i32_e32 vcc, v2, v148
	v_or_b32_e32 v0, 6, v16
	v_lshl_add_u32 v4, v0, 2, s3
	v_cndmask_b32_e32 v24, 0, v3, vcc
	ds_read_b64 v[2:3], v14 offset:512
	ds_read_b32 v14, v18
	ds_read_b32 v18, v4
	ds_read_b64 v[26:27], v4 offset:512
	s_waitcnt lgkmcnt(5)
	v_mul_f32_e32 v23, v22, v34
	v_mov_b32_e32 v22, v21
	s_waitcnt lgkmcnt(3)
	v_pk_mul_f32 v[2:3], v[24:25], v[2:3]
	s_nop 0
	v_cvt_pk_bf16_f32 v2, v2, v3
	v_and_b32_e32 v36, 0xffff0000, v2
	v_lshlrev_b32_e32 v37, 16, v2
	v_or_b32_e32 v2, 7, v16
	v_cmp_le_i32_e32 vcc, v2, v149
	s_waitcnt lgkmcnt(2)
	v_mul_f32_e32 v29, v14, v36
	v_mov_b32_e32 v14, v12
	v_cndmask_b32_e32 v31, 0, v6, vcc
	v_cmp_le_i32_e32 vcc, v0, v148
	v_pk_add_f32 v[10:11], v[10:11], v[14:15]
	v_mul_f32_e32 v3, v28, v37
	v_cndmask_b32_e32 v30, 0, v5, vcc
	s_waitcnt lgkmcnt(0)
	v_pk_mul_f32 v[4:5], v[30:31], v[26:27]
	v_lshl_add_u32 v28, v2, 2, s3
	v_cvt_pk_bf16_f32 v0, v4, v5
	v_lshlrev_b32_e32 v26, 16, v0
	v_mul_f32_e32 v5, v18, v26
	v_mov_b32_e32 v18, v13
	v_and_b32_e32 v6, 0xffff0000, v0
	v_pk_add_f32 v[10:11], v[18:19], v[10:11]
	v_mov_b32_e32 v0, v20
	v_pk_add_f32 v[0:1], v[0:1], v[10:11]
	v_mov_b32_e32 v2, v24
	v_pk_add_f32 v[0:1], v[22:23], v[0:1]
	v_mov_b32_e32 v4, v30
	v_pk_add_f32 v[0:1], v[2:3], v[0:1]
	ds_read_b32 v2, v28
	v_mov_b32_e32 v28, v25
	v_pk_add_f32 v[0:1], v[28:29], v[0:1]
	v_add_u32_e32 v16, 8, v16
	v_pk_add_f32 v[0:1], v[4:5], v[0:1]
	s_waitcnt lgkmcnt(0)
	v_mul_f32_e32 v3, v2, v6
	v_mov_b32_e32 v2, v31
	v_pk_add_f32 v[10:11], v[2:3], v[0:1]
	v_cvt_pk_bf16_f32 v0, v33, v32
	v_cvt_pk_bf16_f32 v1, v35, v34
	v_cvt_pk_bf16_f32 v2, v37, v36
	v_cvt_pk_bf16_f32 v3, v26, v6
	ds_write_b128 v17, v[0:3]
	v_add_u32_e32 v17, 16, v17

.LBB0_199:
	s_waitcnt vmcnt(8) lgkmcnt(0)
	v_ashrrev_i32_e32 v250, 4, v153
	v_mul_lo_u32 v250, v250, s15
	v_add_u32_e32 v250, v250, v152
	s_lshl_b32 s48, s15, 5
	ds_write_b128 v250, v[64:67] offset:18432
	v_add_u32_e32 v250, s48, v250
	ds_write_b128 v250, v[68:71] offset:18432
	v_add_u32_e32 v250, s48, v250
	ds_write_b128 v250, v[72:75] offset:18432
	v_add_u32_e32 v250, s48, v250
	ds_write_b128 v250, v[76:79] offset:18432
	v_add_u32_e32 v250, s48, v250
	ds_write_b128 v250, v[80:83] offset:18432
	v_add_u32_e32 v250, s48, v250
	ds_write_b128 v250, v[84:87] offset:18432
	v_add_u32_e32 v250, s48, v250
	ds_write_b128 v250, v[88:91] offset:18432
	v_add_u32_e32 v250, s48, v250
	ds_write_b128 v250, v[92:95] offset:18432
	s_movk_i32 s22, 0x1000
	s_waitcnt lgkmcnt(0)
	s_barrier
	ds_read_b128 v[0:3], v154
	ds_read_b128 v[8:11], v155 offset:18432
	ds_read_b128 v[136:139], v154 offset:32
	ds_read_b128 v[12:15], v155 offset:18464
	ds_read_b128 v[4:7], v154 offset:4608
	ds_read_b128 v[132:135], v154 offset:4640
	s_waitcnt lgkmcnt(4)
	v_mfma_f32_32x32x16_bf16 v[48:63], v[0:3], v[8:11], 0
	s_and_b32 s16, s41, 7
	s_lshl_b32 s12, s12, 1
	s_lshl_b32 s16, s16, 1
	s_and_b32 s12, s12, 0x1fffff0
	s_and_b32 s17, s43, 1
	s_or_b32 s12, s12, s16
	s_or_b32 s12, s12, s17
	s_waitcnt lgkmcnt(1)
	v_mfma_f32_32x32x16_bf16 v[32:47], v[4:7], v[8:11], 0
	s_mov_b64 s[16:17], 0
	v_mfma_f32_32x32x16_bf16 v[48:63], v[136:139], v[12:15], v[48:63]
	s_waitcnt lgkmcnt(0)
	v_mfma_f32_32x32x16_bf16 v[32:47], v[132:135], v[12:15], v[32:47]
	ds_read_b128 v[128:131], v154 offset:64
	ds_read_b128 v[8:11], v155 offset:18496
	ds_read_b128 v[116:119], v154 offset:96
	ds_read_b128 v[12:15], v155 offset:18528
	ds_read_b128 v[124:127], v154 offset:4672
	ds_read_b128 v[112:115], v154 offset:4704
	s_waitcnt lgkmcnt(4)
	v_mfma_f32_32x32x16_bf16 v[48:63], v[128:131], v[8:11], v[48:63]
	s_waitcnt lgkmcnt(1)
	v_mfma_f32_32x32x16_bf16 v[32:47], v[124:127], v[8:11], v[32:47]
	v_mfma_f32_32x32x16_bf16 v[48:63], v[116:119], v[12:15], v[48:63]
	s_waitcnt lgkmcnt(0)
	v_mfma_f32_32x32x16_bf16 v[32:47], v[112:115], v[12:15], v[32:47]
	ds_read_b128 v[108:111], v154 offset:55296
	ds_read_b128 v[8:11], v180
	ds_read_b128 v[12:15], v180 offset:32
	ds_read_b128 v[92:95], v154 offset:55328
	ds_read_b128 v[100:103], v154 offset:59904
	ds_read_b128 v[88:91], v154 offset:59936
	ds_read_b128 v[84:87], v154 offset:55360
	s_waitcnt lgkmcnt(5)
	v_mfma_f32_32x32x16_bf16 v[48:63], v[108:111], v[8:11], v[48:63]
	s_waitcnt lgkmcnt(2)
	v_mfma_f32_32x32x16_bf16 v[32:47], v[100:103], v[8:11], v[32:47]
	v_mfma_f32_32x32x16_bf16 v[48:63], v[92:95], v[12:15], v[48:63]
	s_waitcnt lgkmcnt(1)
	v_mfma_f32_32x32x16_bf16 v[32:47], v[88:91], v[12:15], v[32:47]
	ds_read_b128 v[12:15], v180 offset:64
	ds_read_b128 v[72:75], v154 offset:59968
	ds_read_b128 v[80:83], v154 offset:55392
	ds_read_b128 v[16:19], v180 offset:96
	ds_read_b128 v[8:11], v155 offset:23040
	ds_read_b128 v[144:147], v155 offset:23072
	ds_read_b128 v[140:143], v155 offset:23104
	ds_read_b128 v[120:123], v155 offset:23136
	ds_read_b128 v[104:107], v180 offset:4608
	ds_read_b128 v[96:99], v180 offset:4640
	ds_read_b128 v[64:67], v154 offset:60000
	ds_read_b128 v[76:79], v180 offset:4672
	ds_read_b128 v[68:71], v180 offset:4704
	s_waitcnt lgkmcnt(0)
	s_barrier
	v_mfma_f32_32x32x16_bf16 v[48:63], v[84:87], v[12:15], v[48:63]
	v_mfma_f32_32x32x16_bf16 v[32:47], v[72:75], v[12:15], v[32:47]
	v_lshl_add_u32 v12, s12, 7, v178
	v_ashrrev_i32_e32 v13, 31, v12
	v_lshlrev_b64 v[12:13], 12, v[12:13]
	v_lshl_or_b32 v12, s18, 9, v12
	v_lshl_add_u64 v[168:169], v[166:167], 0, v[12:13]
	v_mov_b32_e32 v12, v192
	v_mfma_f32_32x32x16_bf16 v[48:63], v[80:83], v[16:19], v[48:63]
	v_mfma_f32_32x32x16_bf16 v[32:47], v[64:67], v[16:19], v[32:47]

.LBB0_1563:
	s_ashr_i32 s10, s26, 4
	s_and_b32 s14, s26, 7
	s_and_b32 s15, s10, 0x7ffffff8
	s_or_b32 s14, s15, s14
	s_lshl_b32 s14, s14, 1
	s_bfe_u32 s15, s26, 0x10006
	s_or_b32 s14, s14, s15
	s_and_saveexec_b64 s[16:17], s[0:1]
	s_cbranch_execz .Lg3_1563_nl
	v_lshl_add_u32 v0, s14, 7, v153
	v_ashrrev_i32_e32 v1, 31, v0
	v_lshlrev_b64 v[0:1], 8, v[0:1]
	v_lshl_add_u64 v[60:61], s[8:9], 0, v[0:1]
	global_load_dwordx4 v[0:3], v[60:61], off
	global_load_dwordx4 v[4:7], v[60:61], off offset:16
	global_load_dwordx4 v[8:11], v[60:61], off offset:32
	global_load_dwordx4 v[12:15], v[60:61], off offset:48
	global_load_dwordx4 v[16:19], v[60:61], off offset:64
	global_load_dwordx4 v[20:23], v[60:61], off offset:80
	global_load_dwordx4 v[24:27], v[60:61], off offset:96
	global_load_dwordx4 v[28:31], v[60:61], off offset:112
	global_load_dwordx4 v[32:35], v[60:61], off offset:128
	global_load_dwordx4 v[36:39], v[60:61], off offset:144
	global_load_dwordx4 v[40:43], v[60:61], off offset:160
	global_load_dwordx4 v[44:47], v[60:61], off offset:176
	global_load_dwordx4 v[48:51], v[60:61], off offset:192
	global_load_dwordx4 v[52:55], v[60:61], off offset:208
	global_load_dwordx4 v[56:59], v[60:61], off offset:224
	s_nop 0
	global_load_dwordx4 v[60:63], v[60:61], off offset:240
.Lg3_1563_nl:
	s_or_b64 exec, exec, s[16:17]
	s_lshl_b32 s16, s26, 4
	s_and_b32 s16, s16, 0x380
	v_add_u32_e32 v248, s16, v148
	v_ashrrev_i32_e32 v249, 31, v248
	v_lshlrev_b64 v[248:249], 9, v[248:249]
	v_lshl_add_u64 v[248:249], v[164:165], 0, v[248:249]
	global_load_dwordx4 v[96:99], v[248:249], off
	global_load_dwordx4 v[100:103], v[248:249], off offset:16
	global_load_dwordx4 v[104:107], v[248:249], off offset:32
	global_load_dwordx4 v[108:111], v[248:249], off offset:48
	global_load_dwordx4 v[112:115], v[248:249], off offset:64
	global_load_dwordx4 v[116:119], v[248:249], off offset:80
	global_load_dwordx4 v[120:123], v[248:249], off offset:96
	global_load_dwordx4 v[124:127], v[248:249], off offset:112
	s_lshr_b32 s17, s26, 3
	s_and_b32 s17, s17, 7
	s_lshl_b32 s16, s14, 11
	s_lshl_b32 s18, s17, 8
	s_or_b32 s16, s16, s18
	v_ashrrev_i32_e32 v250, 4, v153
	v_add_u32_e32 v250, s16, v250
	v_mov_b32_e32 v251, 0
	v_lshlrev_b64 v[250:251], 8, v[250:251]
	v_lshl_add_u64 v[250:251], v[150:151], 0, v[250:251]
	s_movk_i32 s18, 0x2000
	s_mov_b32 s19, 0
	global_load_dwordx4 v[64:67], v[250:251], off
	v_lshl_add_u64 v[250:251], v[250:251], 0, s[18:19]
	global_load_dwordx4 v[68:71], v[250:251], off
	v_lshl_add_u64 v[250:251], v[250:251], 0, s[18:19]
	global_load_dwordx4 v[72:75], v[250:251], off
	v_lshl_add_u64 v[250:251], v[250:251], 0, s[18:19]
	global_load_dwordx4 v[76:79], v[250:251], off
	v_lshl_add_u64 v[250:251], v[250:251], 0, s[18:19]
	global_load_dwordx4 v[80:83], v[250:251], off
	v_lshl_add_u64 v[250:251], v[250:251], 0, s[18:19]
	global_load_dwordx4 v[84:87], v[250:251], off
	v_lshl_add_u64 v[250:251], v[250:251], 0, s[18:19]
	global_load_dwordx4 v[88:91], v[250:251], off
	v_lshl_add_u64 v[250:251], v[250:251], 0, s[18:19]
	global_load_dwordx4 v[92:95], v[250:251], off
	v_lshl_add_u32 v248, s14, 7, v178
	v_ashrrev_i32_e32 v249, 31, v248
	v_lshlrev_b64 v[248:249], 12, v[248:249]
	v_lshl_or_b32 v248, s17, 9, v248
	v_lshl_add_u64 v[248:249], v[166:167], 0, v[248:249]
	s_mov_b32 s18, 0x6000000
	v_lshl_add_u64 v[248:249], v[248:249], 0, s[18:19]
	s_mov_b32 s18, 0x8000
	global_load_dwordx4 v[216:219], v[248:249], off
	v_lshl_add_u64 v[248:249], v[248:249], 0, s[18:19]
	global_load_dwordx4 v[220:223], v[248:249], off
	v_lshl_add_u64 v[248:249], v[248:249], 0, s[18:19]
	global_load_dwordx4 v[224:227], v[248:249], off
	v_lshl_add_u64 v[248:249], v[248:249], 0, s[18:19]
	global_load_dwordx4 v[228:231], v[248:249], off
	v_lshl_add_u64 v[248:249], v[248:249], 0, s[18:19]
	global_load_dwordx4 v[232:235], v[248:249], off
	v_lshl_add_u64 v[248:249], v[248:249], 0, s[18:19]
	global_load_dwordx4 v[236:239], v[248:249], off
	v_lshl_add_u64 v[248:249], v[248:249], 0, s[18:19]
	global_load_dwordx4 v[240:243], v[248:249], off
	v_lshl_add_u64 v[248:249], v[248:249], 0, s[18:19]
	global_load_dwordx4 v[244:247], v[248:249], off
	s_waitcnt vmcnt(63) expcnt(7) lgkmcnt(15)
	s_barrier
	s_and_saveexec_b64 s[16:17], s[0:1]
	s_cbranch_execz .LBB0_1565
	s_waitcnt vmcnt(39)
	v_pk_add_f32 v[0:1], v[0:1], 0 op_sel_hi:[1,0]
	s_nop 0
	v_pk_add_f32 v[0:1], v[0:1], v[2:3]
	s_waitcnt vmcnt(38)
	v_pk_add_f32 v[0:1], v[0:1], v[4:5]
	s_nop 0
	v_pk_add_f32 v[0:1], v[0:1], v[6:7]
	s_waitcnt vmcnt(37)
	v_pk_add_f32 v[0:1], v[0:1], v[8:9]
	s_nop 0
	v_pk_add_f32 v[0:1], v[0:1], v[10:11]
	s_waitcnt vmcnt(36)
	v_pk_add_f32 v[0:1], v[0:1], v[12:13]
	s_nop 0
	v_pk_add_f32 v[0:1], v[0:1], v[14:15]
	s_waitcnt vmcnt(35)
	v_pk_add_f32 v[0:1], v[0:1], v[16:17]
	s_nop 0
	v_pk_add_f32 v[0:1], v[0:1], v[18:19]
	s_waitcnt vmcnt(34)
	v_pk_add_f32 v[0:1], v[0:1], v[20:21]
	s_nop 0
	v_pk_add_f32 v[0:1], v[0:1], v[22:23]
	s_waitcnt vmcnt(33)
	v_pk_add_f32 v[0:1], v[0:1], v[24:25]
	s_nop 0
	v_pk_add_f32 v[0:1], v[0:1], v[26:27]
	s_waitcnt vmcnt(32)
	v_pk_add_f32 v[0:1], v[0:1], v[28:29]
	s_nop 0
	v_pk_add_f32 v[0:1], v[0:1], v[30:31]
	s_waitcnt vmcnt(31)
	v_pk_add_f32 v[0:1], v[0:1], v[32:33]
	s_nop 0
	v_pk_add_f32 v[0:1], v[0:1], v[34:35]
	s_waitcnt vmcnt(30)
	v_pk_add_f32 v[0:1], v[0:1], v[36:37]
	s_nop 0
	v_pk_add_f32 v[0:1], v[0:1], v[38:39]
	s_waitcnt vmcnt(29)
	v_pk_add_f32 v[0:1], v[0:1], v[40:41]
	s_nop 0
	v_pk_add_f32 v[0:1], v[0:1], v[42:43]
	s_waitcnt vmcnt(28)
	v_pk_add_f32 v[0:1], v[0:1], v[44:45]
	s_nop 0
	v_pk_add_f32 v[0:1], v[0:1], v[46:47]
	s_waitcnt vmcnt(27)
	v_pk_add_f32 v[0:1], v[0:1], v[48:49]
	s_nop 0
	v_pk_add_f32 v[0:1], v[0:1], v[50:51]
	s_waitcnt vmcnt(26)
	v_pk_add_f32 v[0:1], v[0:1], v[52:53]
	s_nop 0
	v_pk_add_f32 v[0:1], v[0:1], v[54:55]
	s_waitcnt vmcnt(25)
	v_pk_add_f32 v[0:1], v[0:1], v[56:57]
	s_nop 0
	v_pk_add_f32 v[0:1], v[0:1], v[58:59]
	s_waitcnt vmcnt(24)
	v_pk_add_f32 v[0:1], v[0:1], v[60:61]
	s_nop 0
	v_pk_add_f32 v[0:1], v[0:1], v[62:63]
	s_nop 0
	v_pk_mul_f32 v[0:1], v[0:1], s[12:13] op_sel_hi:[1,0]
	s_nop 0
	v_fma_f32 v1, -v0, v0, v1
	v_max_f32_e32 v1, 0, v1
	v_add_f32_e32 v1, 0x358637bd, v1
	v_mul_f32_e32 v2, 0x4b800000, v1
	v_cmp_gt_f32_e32 vcc, s22, v1
	s_nop 1
	v_cndmask_b32_e32 v1, v1, v2, vcc
	v_rsq_f32_e32 v1, v1
	s_nop 0
	v_mul_f32_e32 v2, 0x45800000, v1
	v_cndmask_b32_e32 v1, v1, v2, vcc
	ds_write2st64_b32 v172, v0, v1 offset1:2
.LBB0_1565:
	s_or_b64 exec, exec, s[16:17]
	s_lshl_b32 s16, s26, 4
	s_and_b32 s16, s16, 0x380
	v_add_u32_e32 v0, s16, v148
	v_ashrrev_i32_e32 v1, 31, v0
	v_lshlrev_b64 v[0:1], 9, v[0:1]
	v_mov_b32_e32 v10, 0
	s_lshr_b32 s27, s26, 6
	s_lshr_b32 s15, s26, 3
	v_lshl_add_u64 v[8:9], v[164:165], 0, v[0:1]
	s_mov_b64 s[16:17], 0
	v_mov_b32_e32 v7, v191
	v_mov_b32_e32 v16, v173
	v_mov_b32_e32 v17, v174
	v_mov_b32_e32 v11, v10
	s_waitcnt lgkmcnt(0)
	s_barrier
	s_waitcnt vmcnt(16)
	v_cmp_le_i32_e32 vcc, v16, v148
	v_mov_b32_e32 v0, v97
	v_mov_b32_e32 v1, v98
	v_mov_b32_e32 v2, v99
	v_mov_b32_e32 v3, v100
	v_mov_b32_e32 v4, v101
	v_mov_b32_e32 v5, v102
	v_mov_b32_e32 v6, v103
	v_cndmask_b32_e32 v12, 0, v96, vcc
	ds_read2st64_b64 v[18:21], v7 offset1:1
	v_cmp_lt_i32_e32 vcc, v16, v148
	s_add_u32 s16, s16, 32
	s_addc_u32 s17, s17, 0
	s_waitcnt vmcnt(16)
	v_cndmask_b32_e32 v13, 0, v0, vcc
	s_waitcnt lgkmcnt(0)
	v_pk_mul_f32 v[14:15], v[12:13], v[20:21]
	s_cmpk_eq_i32 s16, 0x80
	v_cvt_pk_bf16_f32 v0, v14, v15
	v_and_b32_e32 v32, 0xffff0000, v0
	v_lshlrev_b32_e32 v33, 16, v0
	v_or_b32_e32 v0, 3, v16
	v_or_b32_e32 v14, 2, v16
	v_cmp_le_i32_e32 vcc, v0, v149
	v_mul_f32_e32 v15, v18, v33
	v_lshl_add_u32 v18, v14, 2, s3
	v_cndmask_b32_e32 v21, 0, v2, vcc
	v_cmp_le_i32_e32 vcc, v14, v148
	v_lshl_add_u32 v22, v0, 2, s3
	v_or_b32_e32 v2, 4, v16
	v_cndmask_b32_e32 v20, 0, v1, vcc
	ds_read_b64 v[0:1], v18 offset:512
	v_lshl_add_u32 v14, v2, 2, s3
	ds_read_b32 v18, v18
	ds_read_b32 v22, v22
	ds_read_b32 v28, v14
	v_mul_f32_e32 v19, v19, v32
	v_add_u32_e32 v7, 32, v7
	s_waitcnt lgkmcnt(3)
	v_pk_mul_f32 v[0:1], v[20:21], v[0:1]
	s_nop 0
	v_cvt_pk_bf16_f32 v0, v0, v1
	v_and_b32_e32 v34, 0xffff0000, v0
	v_lshlrev_b32_e32 v35, 16, v0
	v_or_b32_e32 v0, 5, v16
	v_cmp_le_i32_e32 vcc, v0, v149
	s_waitcnt lgkmcnt(2)
	v_mul_f32_e32 v1, v18, v35
	v_lshl_add_u32 v18, v0, 2, s3
	v_cndmask_b32_e32 v25, 0, v4, vcc
	v_cmp_le_i32_e32 vcc, v2, v148
	v_or_b32_e32 v0, 6, v16
	v_lshl_add_u32 v4, v0, 2, s3
	v_cndmask_b32_e32 v24, 0, v3, vcc
	ds_read_b64 v[2:3], v14 offset:512
	ds_read_b32 v14, v18
	ds_read_b32 v18, v4
	ds_read_b64 v[26:27], v4 offset:512
	s_waitcnt lgkmcnt(5)
	v_mul_f32_e32 v23, v22, v34
	v_mov_b32_e32 v22, v21
	s_waitcnt lgkmcnt(3)
	v_pk_mul_f32 v[2:3], v[24:25], v[2:3]
	s_nop 0
	v_cvt_pk_bf16_f32 v2, v2, v3
	v_and_b32_e32 v36, 0xffff0000, v2
	v_lshlrev_b32_e32 v37, 16, v2
	v_or_b32_e32 v2, 7, v16
	v_cmp_le_i32_e32 vcc, v2, v149
	s_waitcnt lgkmcnt(2)
	v_mul_f32_e32 v29, v14, v36
	v_mov_b32_e32 v14, v12
	v_cndmask_b32_e32 v31, 0, v6, vcc
	v_cmp_le_i32_e32 vcc, v0, v148
	v_pk_add_f32 v[10:11], v[10:11], v[14:15]
	v_mul_f32_e32 v3, v28, v37
	v_cndmask_b32_e32 v30, 0, v5, vcc
	s_waitcnt lgkmcnt(0)
	v_pk_mul_f32 v[4:5], v[30:31], v[26:27]
	v_lshl_add_u32 v28, v2, 2, s3
	v_cvt_pk_bf16_f32 v0, v4, v5
	v_lshlrev_b32_e32 v26, 16, v0
	v_mul_f32_e32 v5, v18, v26
	v_mov_b32_e32 v18, v13
	v_and_b32_e32 v6, 0xffff0000, v0
	v_pk_add_f32 v[10:11], v[18:19], v[10:11]
	v_mov_b32_e32 v0, v20
	v_pk_add_f32 v[0:1], v[0:1], v[10:11]
	v_mov_b32_e32 v2, v24
	v_pk_add_f32 v[0:1], v[22:23], v[0:1]
	v_mov_b32_e32 v4, v30
	v_pk_add_f32 v[0:1], v[2:3], v[0:1]
	ds_read_b32 v2, v28
	v_mov_b32_e32 v28, v25
	v_pk_add_f32 v[0:1], v[28:29], v[0:1]
	v_add_u32_e32 v16, 8, v16
	v_pk_add_f32 v[0:1], v[4:5], v[0:1]
	s_waitcnt lgkmcnt(0)
	v_mul_f32_e32 v3, v2, v6
	v_mov_b32_e32 v2, v31
	v_pk_add_f32 v[10:11], v[2:3], v[0:1]
	v_cvt_pk_bf16_f32 v0, v33, v32
	v_cvt_pk_bf16_f32 v1, v35, v34
	v_cvt_pk_bf16_f32 v2, v37, v36
	v_cvt_pk_bf16_f32 v3, v26, v6
	ds_write_b128 v17, v[0:3]
	v_add_u32_e32 v17, 16, v17
	v_cmp_le_i32_e32 vcc, v16, v148
	v_mov_b32_e32 v0, v105
	v_mov_b32_e32 v1, v106
	v_mov_b32_e32 v2, v107
	v_mov_b32_e32 v3, v108
	v_mov_b32_e32 v4, v109
	v_mov_b32_e32 v5, v110
	v_mov_b32_e32 v6, v111
	v_cndmask_b32_e32 v12, 0, v104, vcc
	ds_read2st64_b64 v[18:21], v7 offset1:1
	v_cmp_lt_i32_e32 vcc, v16, v148
	s_add_u32 s16, s16, 32
	s_addc_u32 s17, s17, 0
	s_waitcnt vmcnt(16)
	v_cndmask_b32_e32 v13, 0, v0, vcc
	s_waitcnt lgkmcnt(0)
	v_pk_mul_f32 v[14:15], v[12:13], v[20:21]
	s_cmpk_eq_i32 s16, 0x80
	v_cvt_pk_bf16_f32 v0, v14, v15
	v_and_b32_e32 v32, 0xffff0000, v0
	v_lshlrev_b32_e32 v33, 16, v0
	v_or_b32_e32 v0, 3, v16
	v_or_b32_e32 v14, 2, v16
	v_cmp_le_i32_e32 vcc, v0, v149
	v_mul_f32_e32 v15, v18, v33
	v_lshl_add_u32 v18, v14, 2, s3
	v_cndmask_b32_e32 v21, 0, v2, vcc
	v_cmp_le_i32_e32 vcc, v14, v148
	v_lshl_add_u32 v22, v0, 2, s3
	v_or_b32_e32 v2, 4, v16
	v_cndmask_b32_e32 v20, 0, v1, vcc
	ds_read_b64 v[0:1], v18 offset:512
	v_lshl_add_u32 v14, v2, 2, s3
	ds_read_b32 v18, v18
	ds_read_b32 v22, v22
	ds_read_b32 v28, v14
	v_mul_f32_e32 v19, v19, v32
	v_add_u32_e32 v7, 32, v7
	s_waitcnt lgkmcnt(3)
	v_pk_mul_f32 v[0:1], v[20:21], v[0:1]
	s_nop 0
	v_cvt_pk_bf16_f32 v0, v0, v1
	v_and_b32_e32 v34, 0xffff0000, v0
	v_lshlrev_b32_e32 v35, 16, v0
	v_or_b32_e32 v0, 5, v16
	v_cmp_le_i32_e32 vcc, v0, v149
	s_waitcnt lgkmcnt(2)
	v_mul_f32_e32 v1, v18, v35
	v_lshl_add_u32 v18, v0, 2, s3
	v_cndmask_b32_e32 v25, 0, v4, vcc
	v_cmp_le_i32_e32 vcc, v2, v148
	v_or_b32_e32 v0, 6, v16
	v_lshl_add_u32 v4, v0, 2, s3
	v_cndmask_b32_e32 v24, 0, v3, vcc
	ds_read_b64 v[2:3], v14 offset:512
	ds_read_b32 v14, v18
	ds_read_b32 v18, v4
	ds_read_b64 v[26:27], v4 offset:512
	s_waitcnt lgkmcnt(5)
	v_mul_f32_e32 v23, v22, v34
	v_mov_b32_e32 v22, v21
	s_waitcnt lgkmcnt(3)
	v_pk_mul_f32 v[2:3], v[24:25], v[2:3]
	s_nop 0
	v_cvt_pk_bf16_f32 v2, v2, v3
	v_and_b32_e32 v36, 0xffff0000, v2
	v_lshlrev_b32_e32 v37, 16, v2
	v_or_b32_e32 v2, 7, v16
	v_cmp_le_i32_e32 vcc, v2, v149
	s_waitcnt lgkmcnt(2)
	v_mul_f32_e32 v29, v14, v36
	v_mov_b32_e32 v14, v12
	v_cndmask_b32_e32 v31, 0, v6, vcc
	v_cmp_le_i32_e32 vcc, v0, v148
	v_pk_add_f32 v[10:11], v[10:11], v[14:15]
	v_mul_f32_e32 v3, v28, v37
	v_cndmask_b32_e32 v30, 0, v5, vcc
	s_waitcnt lgkmcnt(0)
	v_pk_mul_f32 v[4:5], v[30:31], v[26:27]
	v_lshl_add_u32 v28, v2, 2, s3
	v_cvt_pk_bf16_f32 v0, v4, v5
	v_lshlrev_b32_e32 v26, 16, v0
	v_mul_f32_e32 v5, v18, v26
	v_mov_b32_e32 v18, v13
	v_and_b32_e32 v6, 0xffff0000, v0
	v_pk_add_f32 v[10:11], v[18:19], v[10:11]
	v_mov_b32_e32 v0, v20
	v_pk_add_f32 v[0:1], v[0:1], v[10:11]
	v_mov_b32_e32 v2, v24
	v_pk_add_f32 v[0:1], v[22:23], v[0:1]
	v_mov_b32_e32 v4, v30
	v_pk_add_f32 v[0:1], v[2:3], v[0:1]
	ds_read_b32 v2, v28
	v_mov_b32_e32 v28, v25
	v_pk_add_f32 v[0:1], v[28:29], v[0:1]
	v_add_u32_e32 v16, 8, v16
	v_pk_add_f32 v[0:1], v[4:5], v[0:1]
	s_waitcnt lgkmcnt(0)
	v_mul_f32_e32 v3, v2, v6
	v_mov_b32_e32 v2, v31
	v_pk_add_f32 v[10:11], v[2:3], v[0:1]
	v_cvt_pk_bf16_f32 v0, v33, v32
	v_cvt_pk_bf16_f32 v1, v35, v34
	v_cvt_pk_bf16_f32 v2, v37, v36
	v_cvt_pk_bf16_f32 v3, v26, v6
	ds_write_b128 v17, v[0:3]
	v_add_u32_e32 v17, 16, v17
	v_cmp_le_i32_e32 vcc, v16, v148
	v_mov_b32_e32 v0, v113
	v_mov_b32_e32 v1, v114
	v_mov_b32_e32 v2, v115
	v_mov_b32_e32 v3, v116
	v_mov_b32_e32 v4, v117
	v_mov_b32_e32 v5, v118
	v_mov_b32_e32 v6, v119
	v_cndmask_b32_e32 v12, 0, v112, vcc
	ds_read2st64_b64 v[18:21], v7 offset1:1
	v_cmp_lt_i32_e32 vcc, v16, v148
	s_add_u32 s16, s16, 32
	s_addc_u32 s17, s17, 0
	s_waitcnt vmcnt(16)
	v_cndmask_b32_e32 v13, 0, v0, vcc
	s_waitcnt lgkmcnt(0)
	v_pk_mul_f32 v[14:15], v[12:13], v[20:21]
	s_cmpk_eq_i32 s16, 0x80
	v_cvt_pk_bf16_f32 v0, v14, v15
	v_and_b32_e32 v32, 0xffff0000, v0
	v_lshlrev_b32_e32 v33, 16, v0
	v_or_b32_e32 v0, 3, v16
	v_or_b32_e32 v14, 2, v16
	v_cmp_le_i32_e32 vcc, v0, v149
	v_mul_f32_e32 v15, v18, v33
	v_lshl_add_u32 v18, v14, 2, s3
	v_cndmask_b32_e32 v21, 0, v2, vcc
	v_cmp_le_i32_e32 vcc, v14, v148
	v_lshl_add_u32 v22, v0, 2, s3
	v_or_b32_e32 v2, 4, v16
	v_cndmask_b32_e32 v20, 0, v1, vcc
	ds_read_b64 v[0:1], v18 offset:512
	v_lshl_add_u32 v14, v2, 2, s3
	ds_read_b32 v18, v18
	ds_read_b32 v22, v22
	ds_read_b32 v28, v14
	v_mul_f32_e32 v19, v19, v32
	v_add_u32_e32 v7, 32, v7
	s_waitcnt lgkmcnt(3)
	v_pk_mul_f32 v[0:1], v[20:21], v[0:1]
	s_nop 0
	v_cvt_pk_bf16_f32 v0, v0, v1
	v_and_b32_e32 v34, 0xffff0000, v0
	v_lshlrev_b32_e32 v35, 16, v0
	v_or_b32_e32 v0, 5, v16
	v_cmp_le_i32_e32 vcc, v0, v149
	s_waitcnt lgkmcnt(2)
	v_mul_f32_e32 v1, v18, v35
	v_lshl_add_u32 v18, v0, 2, s3
	v_cndmask_b32_e32 v25, 0, v4, vcc
	v_cmp_le_i32_e32 vcc, v2, v148
	v_or_b32_e32 v0, 6, v16
	v_lshl_add_u32 v4, v0, 2, s3
	v_cndmask_b32_e32 v24, 0, v3, vcc
	ds_read_b64 v[2:3], v14 offset:512
	ds_read_b32 v14, v18
	ds_read_b32 v18, v4
	ds_read_b64 v[26:27], v4 offset:512
	s_waitcnt lgkmcnt(5)
	v_mul_f32_e32 v23, v22, v34
	v_mov_b32_e32 v22, v21
	s_waitcnt lgkmcnt(3)
	v_pk_mul_f32 v[2:3], v[24:25], v[2:3]
	s_nop 0
	v_cvt_pk_bf16_f32 v2, v2, v3
	v_and_b32_e32 v36, 0xffff0000, v2
	v_lshlrev_b32_e32 v37, 16, v2
	v_or_b32_e32 v2, 7, v16
	v_cmp_le_i32_e32 vcc, v2, v149
	s_waitcnt lgkmcnt(2)
	v_mul_f32_e32 v29, v14, v36
	v_mov_b32_e32 v14, v12
	v_cndmask_b32_e32 v31, 0, v6, vcc
	v_cmp_le_i32_e32 vcc, v0, v148
	v_pk_add_f32 v[10:11], v[10:11], v[14:15]
	v_mul_f32_e32 v3, v28, v37
	v_cndmask_b32_e32 v30, 0, v5, vcc
	s_waitcnt lgkmcnt(0)
	v_pk_mul_f32 v[4:5], v[30:31], v[26:27]
	v_lshl_add_u32 v28, v2, 2, s3
	v_cvt_pk_bf16_f32 v0, v4, v5
	v_lshlrev_b32_e32 v26, 16, v0
	v_mul_f32_e32 v5, v18, v26
	v_mov_b32_e32 v18, v13
	v_and_b32_e32 v6, 0xffff0000, v0
	v_pk_add_f32 v[10:11], v[18:19], v[10:11]
	v_mov_b32_e32 v0, v20
	v_pk_add_f32 v[0:1], v[0:1], v[10:11]
	v_mov_b32_e32 v2, v24
	v_pk_add_f32 v[0:1], v[22:23], v[0:1]
	v_mov_b32_e32 v4, v30
	v_pk_add_f32 v[0:1], v[2:3], v[0:1]
	ds_read_b32 v2, v28
	v_mov_b32_e32 v28, v25
	v_pk_add_f32 v[0:1], v[28:29], v[0:1]
	v_add_u32_e32 v16, 8, v16
	v_pk_add_f32 v[0:1], v[4:5], v[0:1]
	s_waitcnt lgkmcnt(0)
	v_mul_f32_e32 v3, v2, v6
	v_mov_b32_e32 v2, v31
	v_pk_add_f32 v[10:11], v[2:3], v[0:1]
	v_cvt_pk_bf16_f32 v0, v33, v32
	v_cvt_pk_bf16_f32 v1, v35, v34
	v_cvt_pk_bf16_f32 v2, v37, v36
	v_cvt_pk_bf16_f32 v3, v26, v6
	ds_write_b128 v17, v[0:3]
	v_add_u32_e32 v17, 16, v17
	v_cmp_le_i32_e32 vcc, v16, v148
	v_mov_b32_e32 v0, v121
	v_mov_b32_e32 v1, v122
	v_mov_b32_e32 v2, v123
	v_mov_b32_e32 v3, v124
	v_mov_b32_e32 v4, v125
	v_mov_b32_e32 v5, v126
	v_mov_b32_e32 v6, v127
	v_cndmask_b32_e32 v12, 0, v120, vcc
	ds_read2st64_b64 v[18:21], v7 offset1:1
	v_cmp_lt_i32_e32 vcc, v16, v148
	s_add_u32 s16, s16, 32
	s_addc_u32 s17, s17, 0
	s_waitcnt vmcnt(16)
	v_cndmask_b32_e32 v13, 0, v0, vcc
	s_waitcnt lgkmcnt(0)
	v_pk_mul_f32 v[14:15], v[12:13], v[20:21]
	s_cmpk_eq_i32 s16, 0x80
	v_cvt_pk_bf16_f32 v0, v14, v15
	v_and_b32_e32 v32, 0xffff0000, v0
	v_lshlrev_b32_e32 v33, 16, v0
	v_or_b32_e32 v0, 3, v16
	v_or_b32_e32 v14, 2, v16
	v_cmp_le_i32_e32 vcc, v0, v149
	v_mul_f32_e32 v15, v18, v33
	v_lshl_add_u32 v18, v14, 2, s3
	v_cndmask_b32_e32 v21, 0, v2, vcc
	v_cmp_le_i32_e32 vcc, v14, v148
	v_lshl_add_u32 v22, v0, 2, s3
	v_or_b32_e32 v2, 4, v16
	v_cndmask_b32_e32 v20, 0, v1, vcc
	ds_read_b64 v[0:1], v18 offset:512
	v_lshl_add_u32 v14, v2, 2, s3
	ds_read_b32 v18, v18
	ds_read_b32 v22, v22
	ds_read_b32 v28, v14
	v_mul_f32_e32 v19, v19, v32
	v_add_u32_e32 v7, 32, v7
	s_waitcnt lgkmcnt(3)
	v_pk_mul_f32 v[0:1], v[20:21], v[0:1]
	s_nop 0
	v_cvt_pk_bf16_f32 v0, v0, v1
	v_and_b32_e32 v34, 0xffff0000, v0
	v_lshlrev_b32_e32 v35, 16, v0
	v_or_b32_e32 v0, 5, v16
	v_cmp_le_i32_e32 vcc, v0, v149
	s_waitcnt lgkmcnt(2)
	v_mul_f32_e32 v1, v18, v35
	v_lshl_add_u32 v18, v0, 2, s3
	v_cndmask_b32_e32 v25, 0, v4, vcc
	v_cmp_le_i32_e32 vcc, v2, v148
	v_or_b32_e32 v0, 6, v16
	v_lshl_add_u32 v4, v0, 2, s3
	v_cndmask_b32_e32 v24, 0, v3, vcc
	ds_read_b64 v[2:3], v14 offset:512
	ds_read_b32 v14, v18
	ds_read_b32 v18, v4
	ds_read_b64 v[26:27], v4 offset:512
	s_waitcnt lgkmcnt(5)
	v_mul_f32_e32 v23, v22, v34
	v_mov_b32_e32 v22, v21
	s_waitcnt lgkmcnt(3)
	v_pk_mul_f32 v[2:3], v[24:25], v[2:3]
	s_nop 0
	v_cvt_pk_bf16_f32 v2, v2, v3
	v_and_b32_e32 v36, 0xffff0000, v2
	v_lshlrev_b32_e32 v37, 16, v2
	v_or_b32_e32 v2, 7, v16
	v_cmp_le_i32_e32 vcc, v2, v149
	s_waitcnt lgkmcnt(2)
	v_mul_f32_e32 v29, v14, v36
	v_mov_b32_e32 v14, v12
	v_cndmask_b32_e32 v31, 0, v6, vcc
	v_cmp_le_i32_e32 vcc, v0, v148
	v_pk_add_f32 v[10:11], v[10:11], v[14:15]
	v_mul_f32_e32 v3, v28, v37
	v_cndmask_b32_e32 v30, 0, v5, vcc
	s_waitcnt lgkmcnt(0)
	v_pk_mul_f32 v[4:5], v[30:31], v[26:27]
	v_lshl_add_u32 v28, v2, 2, s3
	v_cvt_pk_bf16_f32 v0, v4, v5
	v_lshlrev_b32_e32 v26, 16, v0
	v_mul_f32_e32 v5, v18, v26
	v_mov_b32_e32 v18, v13
	v_and_b32_e32 v6, 0xffff0000, v0
	v_pk_add_f32 v[10:11], v[18:19], v[10:11]
	v_mov_b32_e32 v0, v20
	v_pk_add_f32 v[0:1], v[0:1], v[10:11]
	v_mov_b32_e32 v2, v24
	v_pk_add_f32 v[0:1], v[22:23], v[0:1]
	v_mov_b32_e32 v4, v30
	v_pk_add_f32 v[0:1], v[2:3], v[0:1]
	ds_read_b32 v2, v28
	v_mov_b32_e32 v28, v25
	v_pk_add_f32 v[0:1], v[28:29], v[0:1]
	v_add_u32_e32 v16, 8, v16
	v_pk_add_f32 v[0:1], v[4:5], v[0:1]
	s_waitcnt lgkmcnt(0)
	v_mul_f32_e32 v3, v2, v6
	v_mov_b32_e32 v2, v31
	v_pk_add_f32 v[10:11], v[2:3], v[0:1]
	v_cvt_pk_bf16_f32 v0, v33, v32
	v_cvt_pk_bf16_f32 v1, v35, v34
	v_cvt_pk_bf16_f32 v2, v37, v36
	v_cvt_pk_bf16_f32 v3, v26, v6
	ds_write_b128 v17, v[0:3]
	v_add_u32_e32 v17, 16, v17

.LBB0_1572:
	s_waitcnt vmcnt(8) lgkmcnt(0)
	v_ashrrev_i32_e32 v250, 4, v153
	v_mul_lo_u32 v250, v250, s13
	v_add_u32_e32 v250, v250, v152
	s_lshl_b32 s20, s13, 5
	ds_write_b128 v250, v[64:67] offset:18432
	v_add_u32_e32 v250, s20, v250
	ds_write_b128 v250, v[68:71] offset:18432
	v_add_u32_e32 v250, s20, v250
	ds_write_b128 v250, v[72:75] offset:18432
	v_add_u32_e32 v250, s20, v250
	ds_write_b128 v250, v[76:79] offset:18432
	v_add_u32_e32 v250, s20, v250
	ds_write_b128 v250, v[80:83] offset:18432
	v_add_u32_e32 v250, s20, v250
	ds_write_b128 v250, v[84:87] offset:18432
	v_add_u32_e32 v250, s20, v250
	ds_write_b128 v250, v[88:91] offset:18432
	v_add_u32_e32 v250, s20, v250
	ds_write_b128 v250, v[92:95] offset:18432
	s_movk_i32 s18, 0x1000
	s_waitcnt lgkmcnt(0)
	s_barrier
	ds_read_b128 v[0:3], v154
	ds_read_b128 v[8:11], v155 offset:18432
	ds_read_b128 v[136:139], v154 offset:32
	ds_read_b128 v[12:15], v155 offset:18464
	ds_read_b128 v[4:7], v154 offset:4608
	ds_read_b128 v[132:135], v154 offset:4640
	s_waitcnt lgkmcnt(4)
	v_mfma_f32_32x32x16_bf16 v[48:63], v[0:3], v[8:11], 0
	s_and_b32 s14, s23, 7
	s_lshl_b32 s10, s10, 1
	s_lshl_b32 s14, s14, 1
	s_and_b32 s10, s10, 0x1fffff0
	s_and_b32 s15, s27, 1
	s_or_b32 s10, s10, s14
	s_or_b32 s10, s10, s15
	s_waitcnt lgkmcnt(1)
	v_mfma_f32_32x32x16_bf16 v[32:47], v[4:7], v[8:11], 0
	s_mov_b64 s[14:15], 0
	v_mfma_f32_32x32x16_bf16 v[48:63], v[136:139], v[12:15], v[48:63]
	s_waitcnt lgkmcnt(0)
	v_mfma_f32_32x32x16_bf16 v[32:47], v[132:135], v[12:15], v[32:47]
	ds_read_b128 v[128:131], v154 offset:64
	ds_read_b128 v[8:11], v155 offset:18496
	ds_read_b128 v[116:119], v154 offset:96
	ds_read_b128 v[12:15], v155 offset:18528
	ds_read_b128 v[124:127], v154 offset:4672
	ds_read_b128 v[112:115], v154 offset:4704
	s_waitcnt lgkmcnt(4)
	v_mfma_f32_32x32x16_bf16 v[48:63], v[128:131], v[8:11], v[48:63]
	s_waitcnt lgkmcnt(1)
	v_mfma_f32_32x32x16_bf16 v[32:47], v[124:127], v[8:11], v[32:47]
	v_mfma_f32_32x32x16_bf16 v[48:63], v[116:119], v[12:15], v[48:63]
	s_waitcnt lgkmcnt(0)
	v_mfma_f32_32x32x16_bf16 v[32:47], v[112:115], v[12:15], v[32:47]
	ds_read_b128 v[108:111], v154 offset:55296
	ds_read_b128 v[8:11], v180
	ds_read_b128 v[12:15], v180 offset:32
	ds_read_b128 v[92:95], v154 offset:55328
	ds_read_b128 v[100:103], v154 offset:59904
	ds_read_b128 v[88:91], v154 offset:59936
	ds_read_b128 v[84:87], v154 offset:55360
	s_waitcnt lgkmcnt(5)
	v_mfma_f32_32x32x16_bf16 v[48:63], v[108:111], v[8:11], v[48:63]
	s_waitcnt lgkmcnt(2)
	v_mfma_f32_32x32x16_bf16 v[32:47], v[100:103], v[8:11], v[32:47]
	v_mfma_f32_32x32x16_bf16 v[48:63], v[92:95], v[12:15], v[48:63]
	s_waitcnt lgkmcnt(1)
	v_mfma_f32_32x32x16_bf16 v[32:47], v[88:91], v[12:15], v[32:47]
	ds_read_b128 v[12:15], v180 offset:64
	ds_read_b128 v[72:75], v154 offset:59968
	ds_read_b128 v[80:83], v154 offset:55392
	ds_read_b128 v[16:19], v180 offset:96
	ds_read_b128 v[8:11], v155 offset:23040
	ds_read_b128 v[144:147], v155 offset:23072
	ds_read_b128 v[140:143], v155 offset:23104
	ds_read_b128 v[120:123], v155 offset:23136
	ds_read_b128 v[104:107], v180 offset:4608
	ds_read_b128 v[96:99], v180 offset:4640
	ds_read_b128 v[64:67], v154 offset:60000
	ds_read_b128 v[76:79], v180 offset:4672
	ds_read_b128 v[68:71], v180 offset:4704
	s_waitcnt lgkmcnt(0)
	s_barrier
	v_mfma_f32_32x32x16_bf16 v[48:63], v[84:87], v[12:15], v[48:63]
	v_mfma_f32_32x32x16_bf16 v[32:47], v[72:75], v[12:15], v[32:47]
	v_lshl_add_u32 v12, s10, 7, v178
	v_ashrrev_i32_e32 v13, 31, v12
	v_lshlrev_b64 v[12:13], 12, v[12:13]
	v_lshl_or_b32 v12, s16, 9, v12
	v_lshl_add_u64 v[168:169], v[166:167], 0, v[12:13]
	v_mov_b32_e32 v12, v192
	v_mfma_f32_32x32x16_bf16 v[48:63], v[80:83], v[16:19], v[48:63]
	v_mfma_f32_32x32x16_bf16 v[32:47], v[64:67], v[16:19], v[32:47]
